# work-queue fetch: LDS slot via ds_write/ds_read instead of flat sc0 sc1 ops, no vmcnt(0) store drain per item
# baseline (speedup 1.0000x reference)
; #define TIDX opaque_tid()
; #define AIN(i) ((const float*)(__attribute__((address_space(1))) const float*)karg_u64(8 * (i)))
; __device__ __forceinline__ void lds_barrier() { asm volatile("s_waitcnt lgkmcnt(0)\n\ts_barrier" ::: "memory"); }
; #define WSP(T, off) ((T*)(__attribute__((address_space(1))) T*)(launder_ws(AWS, (off))))
; __device__ __forceinline__ void post_item(const Args& a, int l, int it) {
;     const int w = TIDX >> 6, lane = TIDX & 63;
;     const float* P = WSP(const float, WS_P);
;     bf16_t* Y = WSP(bf16_t, WS_Y);
;     const float* nwg = AIN(17) + l * 128; const float* nwh = AIN(19) + l * 128;
;     const float ng0 = nwg[lane], ng1 = nwg[64 + lane], nh0 = nwh[lane], nh1 = nwh[64 + lane];
; #pragma unroll 1
;     for (int tk = 0; tk < 4; ++tk) {
;         const int t = it * 32 + w * 4 + tk;
; __device__ __forceinline__ int fetch_item(unsigned* ctr, unsigned char* lds) {
;     volatile int* slot = (volatile int*)(lds + DYN_LDS - 16);
;     lds_barrier();
;     if (TIDX == 0) *slot = (int)atomicAdd(ctr, 1u);
;     lds_barrier();
;     const int v = *slot;
;     return __builtin_amdgcn_readfirstlane(v);
.LBB0_197:
	s_waitcnt lgkmcnt(0)
	s_barrier
	v_mov_b32_e32 v0, v224
	s_nop 0
	v_cmp_eq_u32_e32 vcc, 0, v0
	s_and_saveexec_b64 s[2:3], vcc
	s_cbranch_execz .LBB0_199
	global_atomic_add v2, v215, v225, s[16:17] sc0
	s_add_i32 s13, 0, 0x22ff0
	s_mov_b64 s[14:15], src_shared_base
	s_cmp_lg_u32 s13, -1
	s_cselect_b32 s13, s13, 0
	s_cselect_b32 s14, s15, 0
	v_mov_b32_e32 v0, s13
	v_mov_b32_e32 v1, s14
	s_waitcnt vmcnt(0)
	ds_write_b32 v0, v2
.LBB0_199:
	s_or_b64 exec, exec, s[2:3]
	s_mov_b64 s[2:3], src_shared_base
	s_add_i32 s2, 0, 0x22ff0
	s_cmp_lg_u32 s2, -1
	s_cselect_b32 s2, s2, 0
	s_cselect_b32 s3, s3, 0
	s_waitcnt lgkmcnt(0)
	s_barrier
	v_mov_b32_e32 v0, s2
	v_mov_b32_e32 v1, s3
	ds_read_b32 v0, v0
	s_mov_b64 s[2:3], -1
	s_waitcnt lgkmcnt(0)
	v_readfirstlane_b32 s13, v0
	s_cmpk_gt_i32 s13, 0x27f
	s_cbranch_scc1 .LBB0_196
	s_cmpk_gt_i32 s13, 0x17f
	s_cbranch_scc0 .LBB0_204
	v_mov_b32_e32 v0, v224
	v_mov_b32_e32 v1, v224
	s_mov_b64 s[2:3], s[0:1]
	s_mov_b64 s[14:15], 0xec18000
	s_mov_b64 s[20:21], s[0:1]
	s_load_dwordx2 s[2:3], s[2:3], 0xd0
	s_mov_b64 s[22:23], 0xcc18000
	s_mov_b64 s[24:25], s[0:1]
	s_load_dwordx2 s[20:21], s[20:21], 0xd0
	s_load_dwordx2 s[24:25], s[24:25], 0x88
	s_mov_b64 s[26:27], s[0:1]
	s_load_dwordx2 s[26:27], s[26:27], 0x98
	v_and_b32_e32 v2, 63, v1
	s_waitcnt lgkmcnt(0)
	s_add_u32 s24, s24, s18
	s_addc_u32 s25, s25, s19
	v_lshlrev_b32_e32 v214, 2, v2
	s_add_u32 s26, s26, s18
	s_addc_u32 s27, s27, s19
	global_load_dword v30, v214, s[24:25]
	global_load_dword v31, v214, s[24:25] offset:256
	global_load_dword v32, v214, s[26:27]
	global_load_dword v33, v214, s[26:27] offset:256
	s_lshl_b32 s24, s13, 5
	v_ashrrev_i32_e32 v0, 4, v0
	v_and_b32_e32 v0, -4, v0
	s_addk_i32 s24, 0xd000
	v_add_u32_e32 v4, s24, v0
	v_ashrrev_i32_e32 v5, 31, v4
	v_lshlrev_b64 v[0:1], 12, v[4:5]
	v_lshl_add_u64 v[0:1], s[22:23], 0, v[0:1]
	v_lshlrev_b32_e32 v2, 1, v2
	v_mov_b32_e32 v3, v215
	s_add_u32 s2, s2, s14
	v_lshl_add_u64 v[0:1], v[0:1], 0, v[2:3]
	s_addc_u32 s3, s3, s15
	v_lshl_add_u64 v[0:1], s[20:21], 0, v[0:1]
	s_movk_i32 s20, 0xa00
	v_mov_b64_e32 v[6:7], s[2:3]
	v_mad_i64_i32 v[2:3], s[20:21], v4, s20, 0
	v_mad_i64_i32 v[4:5], s[2:3], v4, s95, v[6:7]
	s_mov_b64 s[2:3], 0

; #define TIDX opaque_tid()
; __device__ __forceinline__ void lds_barrier() { asm volatile("s_waitcnt lgkmcnt(0)\n\ts_barrier" ::: "memory"); }
; #define WSP(T, off) ((T*)(__attribute__((address_space(1))) T*)(launder_ws(AWS, (off))))
; template <int MODE>
; __device__ __forceinline__ void attn_head(const bf16_t* qptr, const bf16_t* Kg, const bf16_t* Vtg, unsigned long long un, int tok,
;                                           unsigned long long msk, unsigned char* lds, f32x4 (&O)[8], float& lrow) {
;     const int tid = TIDX;
;     bf16x8 qf[4];
; #pragma unroll
;     for (int ks = 0; ks < 4; ++ks) qf[ks] = *(const bf16x8*)(qptr + ks * 32);
;     float mrow = -1e30f; lrow = 0.f;
; #pragma unroll
;     for (int dt = 0; dt < 8; ++dt) O[dt] = zero4();
;     const int n = __builtin_popcountll(un);
;     unsigned long long remc = un, remp = un;
;     int kpre = __builtin_ctzll(remp); remp &= remp - 1;
;     lds_barrier();
;     tile_dma(lds, 0, Kg, Vtg, kpre, tid);
;     if (remp) { kpre = __builtin_ctzll(remp); remp &= remp - 1; }
;     tile_dma(lds, 1, Kg, Vtg, kpre, tid);
; __device__ __forceinline__ void window_item(const Args& a, int it, unsigned char* lds) {
;     const int qt = it & 31, bh = it >> 5, b = bh / 6, hd = bh % 6, g = hd / 3, r = hd % 3, bg = b * 2 + g, t0 = qt * 128;
;     const int tid = TIDX, w = tid >> 6, lane = tid & 63, fr = lane & 15, fq = lane >> 4;
;     const bf16_t* Kg = WSP(const bf16_t, WS_KW) + (size_t)bg * SEQ * 128;
;     const bf16_t* Vtg = WSP(const bf16_t, WS_VWT) + (size_t)bg * 128 * SEQ;
;     const int tokbase = t0 + 16 * w;
;     const bf16_t* qptr = WSP(const bf16_t, WS_QB) + (size_t)(b * SEQ + tokbase + fr) * 768 + hd * 128 + fq * 8;
;     f32x4 O[8]; float lrow;
;     const int kb_lo = (t0 >> 6) >= 8 ? (t0 >> 6) - 8 : 0, kb_hi = (t0 >> 6) + 1;
;     const unsigned long long un = ((kb_hi >= 63) ? ~0ull : ((1ull << (kb_hi + 1)) - 1ull)) & ~((1ull << kb_lo) - 1ull);
;     attn_head<0>(qptr, Kg, Vtg, un, tokbase + fr, 0ull, lds, O, lrow);
; __device__ __forceinline__ int fetch_item(unsigned* ctr, unsigned char* lds) {
;     volatile int* slot = (volatile int*)(lds + DYN_LDS - 16);
;     lds_barrier();
;     if (TIDX == 0) *slot = (int)atomicAdd(ctr, 1u);
;     lds_barrier();
;     const int v = *slot;
;     return __builtin_amdgcn_readfirstlane(v);
.LBB0_223:
	s_waitcnt lgkmcnt(0)
	s_barrier
	s_waitcnt vmcnt(3)
	v_mov_b32_e32 v0, v224
	s_nop 0
	v_cmp_eq_u32_e32 vcc, 0, v0
	s_and_saveexec_b64 s[2:3], vcc
	s_cbranch_execz .LBB0_225
	global_atomic_add v2, v215, v225, s[18:19] sc0
	s_add_i32 s13, 0, 0x22ff0
	s_mov_b64 s[14:15], src_shared_base
	s_cmp_lg_u32 s13, -1
	s_cselect_b32 s13, s13, 0
	s_cselect_b32 s14, s15, 0
	v_mov_b32_e32 v0, s13
	v_mov_b32_e32 v1, s14
	s_waitcnt vmcnt(0)
	ds_write_b32 v0, v2
.LBB0_225:
	s_or_b64 exec, exec, s[2:3]
	s_mov_b64 s[2:3], src_shared_base
	s_add_i32 s2, 0, 0x22ff0
	s_cmp_lg_u32 s2, -1
	s_cselect_b32 s2, s2, 0
	s_cselect_b32 s3, s3, 0
	s_waitcnt lgkmcnt(0)
	s_barrier
	v_mov_b32_e32 v0, s2
	v_mov_b32_e32 v1, s3
	ds_read_b32 v0, v0
	s_mov_b64 s[2:3], -1
	s_waitcnt lgkmcnt(0)
	v_readfirstlane_b32 s13, v0
	s_cmpk_gt_i32 s13, 0x31f
	s_cbranch_scc1 .LBB0_222
	s_cmpk_gt_i32 s13, 0x7f
	s_cbranch_scc0 .LBB0_582
	s_cmpk_gt_u32 s13, 0x11f
	s_cbranch_scc0 .LBB0_524
	s_cmpk_gt_u32 s13, 0x19f
	s_cbranch_scc0 .LBB0_244
	s_add_i32 s15, s13, 0xfffffe60
	s_lshr_b32 s2, s15, 5
	s_add_i32 s3, s2, -6
	s_cmpk_lt_u32 s15, 0xc0
	v_mov_b32_e32 v1, v224
	s_mov_b64 s[20:21], s[0:1]
	s_cselect_b32 s14, s2, s3
	s_cmp_gt_u32 s14, 2
	s_load_dwordx2 s[20:21], s[20:21], 0xd0
	s_cselect_b64 s[2:3], -1, 0
	v_cndmask_b32_e64 v0, 0, 1, s[2:3]
	s_cmpk_gt_u32 s15, 0xbf
	s_cselect_b32 s24, 2, 0
	s_mov_b64 s[22:23], 0x1fc18000
	s_cselect_b32 s38, 0x1000, 0
	v_readfirstlane_b32 s25, v0
	s_lshl_b32 s15, s15, 7
	s_or_b32 s24, s24, s25
	s_and_b32 s15, s15, 0xf80
	s_waitcnt lgkmcnt(0)
	s_add_u32 s22, s20, s22
	s_addc_u32 s23, s21, s23
	s_mov_b64 s[20:21], s[0:1]
	s_load_dwordx2 s[20:21], s[20:21], 0xd0
	s_lshl_b32 s26, s24, 20
	s_add_u32 s22, s22, s26
	s_addc_u32 s23, s23, 0
	s_mov_b64 s[24:25], 0x20418000
	s_waitcnt lgkmcnt(0)
	s_add_u32 s20, s20, s24
	s_addc_u32 s21, s21, s25
	s_add_u32 s24, s20, s26
	s_addc_u32 s25, s21, 0
	s_mov_b64 s[20:21], s[0:1]
	s_load_dwordx2 s[20:21], s[20:21], 0xd0
	v_ashrrev_i32_e32 v0, 2, v1
	v_and_b32_e32 v0, -16, v0
	v_add_u32_e32 v5, s15, v0
	s_mov_b64 s[26:27], 0x1dc18000
	v_and_b32_e32 v4, 15, v1
	v_add_u32_e32 v0, s38, v5
	s_waitcnt lgkmcnt(0)
	s_add_u32 s20, s20, s26
	v_or_b32_e32 v148, v0, v4
	s_movk_i32 s26, 0x300
	s_addc_u32 s21, s21, s27
	v_mad_i64_i32 v[146:147], s[26:27], v148, s26, 0
	v_bfe_u32 v2, v1, 4, 2
	v_lshl_add_u64 v[0:1], v[146:147], 1, s[20:21]
	s_lshl_b32 s92, s14, 8
	v_lshl_add_u64 v[0:1], v[0:1], 0, s[92:93]
	v_lshlrev_b32_e32 v144, 4, v2
	v_mov_b32_e32 v145, v215
	v_lshl_add_u64 v[0:1], v[0:1], 0, v[144:145]
	s_lshr_b32 s20, s15, 6
	v_mov_b32_e32 v8, v224
	s_add_i32 s21, s20, -8
	global_load_dwordx4 v[64:67], v[0:1], off
	global_load_dwordx4 v[68:71], v[0:1], off offset:64
	global_load_dwordx4 v[72:75], v[0:1], off offset:128
	global_load_dwordx4 v[76:79], v[0:1], off offset:192
	v_lshrrev_b32_e32 v0, 6, v8
	s_cmpk_gt_u32 s15, 0x1c0
	v_and_b32_e32 v9, 4, v0
	v_lshrrev_b32_e32 v0, 4, v8
	s_cselect_b32 s26, s21, 0
	s_add_i32 s20, s20, 2
	v_xor_b32_e32 v0, v0, v8
	s_lshl_b64 s[20:21], -1, s20
	v_lshlrev_b32_e32 v0, 3, v0
	s_not_b64 s[20:21], s[20:21]
	v_and_b32_e32 v0, 56, v0
	s_cmpk_lg_i32 s15, 0xf80
	v_lshlrev_b32_e32 v214, 1, v0
	v_ashrrev_i32_e32 v0, 4, v8
	s_cselect_b32 s21, s21, -1
	s_cselect_b32 s20, s20, -1
	s_lshl_b64 s[26:27], -1, s26
	v_lshlrev_b32_e32 v1, 1, v0
	s_and_b64 s[20:21], s[20:21], s[26:27]
	v_xor_b32_e32 v10, v0, v8
	v_and_b32_e32 v1, 24, v1
	v_and_b32_e32 v0, 0xffffffe3, v0
	s_ff1_i32_b64 s15, s[20:21]
	s_add_u32 s26, s20, -1
	v_or3_b32 v150, v0, v1, v9
	s_addc_u32 s27, s21, -1
	s_lshl_b32 s92, s15, 6
	v_ashrrev_i32_e32 v151, 31, v150
	v_lshl_add_u64 v[0:1], s[92:93], 0, v[150:151]
	s_and_b64 s[26:27], s[26:27], s[20:21]
	s_lshl_b32 s38, s15, 7
	v_lshlrev_b64 v[0:1], 8, v[0:1]
	s_add_u32 s38, s24, s38
	v_lshl_add_u64 v[2:3], s[22:23], 0, v[0:1]
	v_lshlrev_b32_e32 v0, 3, v10
	v_lshlrev_b32_e32 v145, 4, v8
	s_addc_u32 s39, s25, 0
	v_and_b32_e32 v0, 0x78, v0
	v_add_u32_e32 v10, 0, v145
	s_mov_b32 s47, s93
	s_mov_b32 s46, s93
	s_mov_b32 s45, s93
	s_mov_b32 s44, s93
	s_mov_b32 s43, s93
	s_mov_b32 s42, s93
	s_mov_b32 s41, s93
	s_mov_b32 s40, s93
	v_lshl_add_u64 v[6:7], s[38:39], 0, v[214:215]
	v_lshlrev_b32_e32 v0, 1, v0
	v_mov_b32_e32 v1, v215
	v_readfirstlane_b32 s38, v10
	s_waitcnt lgkmcnt(0)
	s_barrier
; __device__ __forceinline__ void lds_barrier() { asm volatile("s_waitcnt lgkmcnt(0)\n\ts_barrier" ::: "memory"); }
; __device__ __forceinline__ void tile_dma(unsigned char* lds, int slot, const bf16_t* Kg, const bf16_t* Vtg, int kb, int tid) {
;     unsigned char* kd = lds + slot * RING_SLOT; unsigned char* vd = kd + RING_V;
; #pragma unroll
;     for (int i = 0; i < 2; ++i) {
;         const int q = i * 512 + tid;
;         { const int rs = q >> 4, pos = q & 15, c = pos ^ (rs & 15), nt = rs >> 4, r16 = rs & 15;
;           const int keyl = 32 * (nt >> 1) + 8 * (r16 >> 2) + 4 * (nt & 1) + (r16 & 3);
;           __builtin_amdgcn_global_load_lds((const unsigned*)(Kg + ((size_t)kb * 64 + keyl) * 128 + c * 8),
;                                            (__attribute__((address_space(3))) unsigned*)(kd + q * 16), 16, 0, 0); }
;         { const int d = q >> 3, pos = q & 7, c = pos ^ ((d >> 1) & 7);
;           __builtin_amdgcn_global_load_lds((const unsigned*)(Vtg + (size_t)d * SEQ + kb * 64 + c * 8),
;                                            (__attribute__((address_space(3))) unsigned*)(vd + q * 16), 16, 0, 0); }
;     }
; }
; template <int MODE>
; __device__ __forceinline__ void attn_head(const bf16_t* qptr, const bf16_t* Kg, const bf16_t* Vtg, unsigned long long un, int tok,
;                                           unsigned long long msk, unsigned char* lds, f32x4 (&O)[8], float& lrow) {
;     ...
;     float mrow = -1e30f; lrow = 0.f;
; #pragma unroll
;     for (int dt = 0; dt < 8; ++dt) O[dt] = zero4();
;     const int n = __builtin_popcountll(un);
;     unsigned long long remc = un, remp = un;
;     int kpre = __builtin_ctzll(remp); remp &= remp - 1;
;     lds_barrier();
;     tile_dma(lds, 0, Kg, Vtg, kpre, tid);
;     if (remp) { kpre = __builtin_ctzll(remp); remp &= remp - 1; }
;     tile_dma(lds, 1, Kg, Vtg, kpre, tid);
	v_lshl_add_u64 v[2:3], v[2:3], 0, v[0:1]
	s_mov_b32 m0, s38
	v_add_u32_e32 v11, 0x4000, v10
	global_load_lds_dwordx4 v[2:3], off
	v_ashrrev_i32_e32 v2, 3, v8
	v_ashrrev_i32_e32 v3, 31, v2
	v_lshlrev_b64 v[152:153], 13, v[2:3]
	v_readfirstlane_b32 s38, v11
	v_lshl_add_u64 v[2:3], v[6:7], 0, v[152:153]
	s_mov_b32 m0, s38
	v_add_u32_e32 v11, 0x200, v8
	global_load_lds_dwordx4 v[2:3], off
	v_ashrrev_i32_e32 v2, 4, v11
	v_lshlrev_b32_e32 v3, 1, v2
	v_xor_b32_e32 v12, v2, v8
	v_and_b32_e32 v3, 24, v3
	v_and_b32_e32 v2, 0xffffffe3, v2
	v_or3_b32 v154, v2, v3, v9
	v_ashrrev_i32_e32 v155, 31, v154
	v_lshl_add_u64 v[2:3], s[92:93], 0, v[154:155]
	v_lshlrev_b64 v[2:3], 8, v[2:3]
	v_lshl_add_u64 v[8:9], s[22:23], 0, v[2:3]
	v_lshlrev_b32_e32 v2, 3, v12
	v_lshlrev_b32_e32 v149, 4, v11
	v_and_b32_e32 v2, 0x78, v2
	v_add_u32_e32 v12, 0, v149
	v_lshlrev_b32_e32 v2, 1, v2
	v_mov_b32_e32 v3, v215
	v_readfirstlane_b32 s38, v12
	v_lshl_add_u64 v[8:9], v[8:9], 0, v[2:3]
	s_mov_b32 m0, s38
	s_cmp_eq_u64 s[26:27], 0
	global_load_lds_dwordx4 v[8:9], off
	v_ashrrev_i32_e32 v8, 3, v11
	v_ashrrev_i32_e32 v9, 31, v8
	v_lshlrev_b64 v[156:157], 13, v[8:9]
	v_add_u32_e32 v8, 0x4000, v12
	v_lshl_add_u64 v[6:7], v[6:7], 0, v[156:157]
	v_readfirstlane_b32 s38, v8
	s_mov_b32 m0, s38
	s_ff1_i32_b64 s38, s[26:27]
	s_cselect_b32 s15, s15, s38
	s_lshl_b32 s92, s15, 6
	s_lshl_b32 s38, s15, 7
	s_add_u32 s38, s24, s38
	v_lshl_add_u64 v[8:9], s[92:93], 0, v[150:151]
	s_addc_u32 s39, s25, 0
	v_lshlrev_b64 v[8:9], 8, v[8:9]
	v_add_u32_e32 v11, 0x8000, v10
	global_load_lds_dwordx4 v[6:7], off
	v_lshl_add_u64 v[6:7], s[38:39], 0, v[214:215]
	v_lshl_add_u64 v[8:9], s[22:23], 0, v[8:9]
	v_readfirstlane_b32 s38, v11
	v_add_u32_e32 v10, 0xc000, v10
	v_lshl_add_u64 v[8:9], v[8:9], 0, v[0:1]
	s_mov_b32 m0, s38
	v_readfirstlane_b32 s38, v10
	global_load_lds_dwordx4 v[8:9], off
	v_lshl_add_u64 v[8:9], v[6:7], 0, v[152:153]
	s_mov_b32 m0, s38
	v_add_u32_e32 v10, 0x8000, v12
	global_load_lds_dwordx4 v[8:9], off
	v_lshl_add_u64 v[8:9], s[92:93], 0, v[154:155]
	v_lshlrev_b64 v[8:9], 8, v[8:9]
	v_lshl_add_u64 v[8:9], s[22:23], 0, v[8:9]
	v_readfirstlane_b32 s38, v10
	v_lshl_add_u64 v[8:9], v[8:9], 0, v[2:3]
	s_mov_b32 m0, s38
	v_lshl_add_u64 v[6:7], v[6:7], 0, v[156:157]
	global_load_lds_dwordx4 v[8:9], off
	v_add_u32_e32 v8, 0xc000, v12
	s_cmp_lg_u64 s[20:21], 0
	v_readfirstlane_b32 s38, v8
	s_mov_b32 m0, s38
	s_nop 0
	global_load_lds_dwordx4 v[6:7], off
	s_cbranch_scc0 .LBB0_591
	s_bcnt1_i32_b64 s38, s[20:21]
	v_lshl_add_u64 v[160:161], s[22:23], 0, v[0:1]
	v_lshl_add_u64 v[162:163], s[22:23], 0, v[2:3]
	s_add_u32 s22, s26, -1
	v_or_b32_e32 v164, v5, v4
	s_addc_u32 s23, s27, -1
	v_lshl_add_u64 v[158:159], s[24:25], 0, v[214:215]
	s_and_b64 s[22:23], s[22:23], s[26:27]
	v_add_u32_e32 v165, 0xfffffe00, v164
	v_mov_b32_e32 v167, 0xf149f2ca
	s_mov_b32 s39, 0
	v_mov_b32_e32 v166, 0
	v_mov_b32_e32 v60, s47
	v_mov_b32_e32 v61, s47
	v_mov_b32_e32 v62, s47
	v_mov_b32_e32 v63, s47
	v_mov_b32_e32 v56, s46
	v_mov_b32_e32 v57, s46
	v_mov_b32_e32 v58, s46
	v_mov_b32_e32 v59, s46
	v_mov_b32_e32 v52, s45
	v_mov_b32_e32 v53, s45
	v_mov_b32_e32 v54, s45
	v_mov_b32_e32 v55, s45
	v_mov_b32_e32 v48, s44
	v_mov_b32_e32 v49, s44
	v_mov_b32_e32 v50, s44
	v_mov_b32_e32 v51, s44
	v_mov_b32_e32 v44, s43
	v_mov_b32_e32 v45, s43
	v_mov_b32_e32 v46, s43
	v_mov_b32_e32 v47, s43
	v_mov_b32_e32 v40, s42
	v_mov_b32_e32 v41, s42
	v_mov_b32_e32 v42, s42
	v_mov_b32_e32 v43, s42
	v_mov_b32_e32 v36, s41
	v_mov_b32_e32 v37, s41
	v_mov_b32_e32 v38, s41
	v_mov_b32_e32 v39, s41
	v_mov_b32_e32 v32, s40
	v_mov_b32_e32 v33, s40
	v_mov_b32_e32 v34, s40
	v_mov_b32_e32 v35, s40
	s_waitcnt vmcnt(0)

; #define TIDX opaque_tid()
; __device__ __forceinline__ void lds_barrier() { asm volatile("s_waitcnt lgkmcnt(0)\n\ts_barrier" ::: "memory"); }
; __device__ __forceinline__ int fetch_item(unsigned* ctr, unsigned char* lds) {
;     volatile int* slot = (volatile int*)(lds + DYN_LDS - 16);
;     lds_barrier();
;     if (TIDX == 0) *slot = (int)atomicAdd(ctr, 1u);
;     lds_barrier();
;     const int v = *slot;
;     return __builtin_amdgcn_readfirstlane(v);
;     ...
;         while (true) {
;             const int it = fetch_item(ctl + 128 + l, lds);
;             if (it >= 640 + 640 + 512 + 256) break;
;             if (it < 640) { if (sub & 1) gdn_chunk(a, l, it, lds); }
;             else if (it < 1280) { if (sub & 2) hgrn_chunk(a, l, it - 640, lds); }
;             else if (it < 1792) { if (sub & 4) vtrans_item(a, it - 1280, lds); }
;             else { if (sub & 8) { for (int q = 0; q < 4; ++q) nsa_prep_token(a, (it - 1792) * 32 + q * 8 + (TIDX >> 6), TIDX & 63); } }
.LBB0_606:
	s_or_b64 exec, exec, s[16:17]
	s_waitcnt vmcnt(0)
	v_readfirstlane_b32 s13, v1
	s_mov_b64 s[14:15], src_shared_base
	s_nop 0
	v_add_u32_e32 v2, s13, v0
	s_add_i32 s13, 0, 0x22ff0
	s_cmp_lg_u32 s13, -1
	s_cselect_b32 s13, s13, 0
	s_cselect_b32 s14, s15, 0
	v_mov_b32_e32 v0, s13
	v_mov_b32_e32 v1, s14
	ds_write_b32 v0, v2
.LBB0_607:
	s_or_b64 exec, exec, s[2:3]
	s_mov_b64 s[2:3], src_shared_base
	s_add_i32 s2, 0, 0x22ff0
	s_cmp_lg_u32 s2, -1
	s_cselect_b32 s2, s2, 0
	s_cselect_b32 s3, s3, 0
	s_waitcnt lgkmcnt(0)
	s_barrier
	v_mov_b32_e32 v0, s2
	v_mov_b32_e32 v1, s3
	ds_read_b32 v0, v0
	s_mov_b64 s[2:3], -1
	s_waitcnt lgkmcnt(0)
	v_readfirstlane_b32 s50, v0
	s_cmpk_gt_i32 s50, 0x7ff
	s_cbranch_scc1 .LBB0_602
	s_cmpk_gt_i32 s50, 0x27f
	s_cbranch_scc0 .LBB0_634
	s_cmpk_gt_u32 s50, 0x4ff
	s_cbranch_scc0 .LBB0_625
	s_cmpk_lt_u32 s50, 0x700
	s_cbranch_scc1 .LBB0_622
	s_lshl_b32 s13, s50, 5
	s_add_i32 s13, s13, 0xffff2000
	s_mov_b32 s14, 0
	s_branch .LBB0_613
